# K-loop LDS-DMA loads use the SGPR-base + 32-bit VGPR offset form (drops 16 64-bit VALU address adds per loop body; kstep-advanced bases built with SALU in s98/s99), on top of DMA-first load blocks
# baseline (speedup 1.0000x reference)
.LBB0_142:
	s_add_u32 s3, s6, 0xfffc0080
	s_addc_u32 s8, s7, -1
	s_cmp_eq_u32 s21, 12
	s_cselect_b32 s11, s17, s8
	s_cselect_b32 s10, s16, s3
	s_cselect_b32 s9, s2, s20
	s_cselect_b32 s8, s4, s5
	s_add_i32 s3, 0, 0x14000
	s_add_i32 m0, s54, 0xc000
	s_nop 0
	global_load_lds_dwordx4 v192, s[6:7]
	s_add_i32 m0, s54, 0xe000
	s_nop 0
	global_load_lds_dwordx4 v194, s[6:7]
	v_add_u32_e32 v106, s63, v17
	v_add_u32_e32 v162, s3, v17
	ds_read_b128 v[22:25], v106
	ds_read_b128 v[26:29], v106 offset:1024
	ds_read_b128 v[102:105], v106 offset:2048
	ds_read_b128 v[106:109], v106 offset:3072
	ds_read_b128 v[150:153], v162
	ds_read_b128 v[154:157], v162 offset:1024
	ds_read_b128 v[158:161], v162 offset:2048
	ds_read_b128 v[162:165], v162 offset:3072
	ds_read_b128 v[166:169], v247
	ds_read_b128 v[170:173], v247 offset:1024
	ds_read_b128 v[174:177], v247 offset:2048
	ds_read_b128 v[178:181], v247 offset:3072
	ds_read_b128 v[182:185], v247 offset:4096
	ds_read_b128 v[196:199], v247 offset:5120
	ds_read_b128 v[200:203], v247 offset:6144
	ds_read_b128 v[204:207], v247 offset:7168
	s_waitcnt vmcnt(8)
	s_waitcnt lgkmcnt(0)
	s_barrier
	s_setprio 1
	s_waitcnt lgkmcnt(0)
	v_mfma_f32_16x16x32_bf16 v[138:141], v[22:25], v[166:169], v[138:141]
	v_mfma_f32_16x16x32_bf16 v[98:101], v[102:105], v[166:169], v[98:101]
	v_mfma_f32_16x16x32_bf16 v[130:133], v[22:25], v[174:177], v[130:133]
	v_mfma_f32_16x16x32_bf16 v[90:93], v[102:105], v[174:177], v[90:93]
	v_mfma_f32_16x16x32_bf16 v[122:125], v[22:25], v[182:185], v[122:125]
	v_mfma_f32_16x16x32_bf16 v[82:85], v[102:105], v[182:185], v[82:85]
	v_mfma_f32_16x16x32_bf16 v[146:149], v[22:25], v[200:203], v[146:149]
	v_mfma_f32_16x16x32_bf16 v[110:113], v[102:105], v[200:203], v[110:113]
	v_mfma_f32_16x16x32_bf16 v[138:141], v[26:29], v[170:173], v[138:141]
	v_mfma_f32_16x16x32_bf16 v[98:101], v[106:109], v[170:173], v[98:101]
	v_mfma_f32_16x16x32_bf16 v[130:133], v[26:29], v[178:181], v[130:133]
	v_mfma_f32_16x16x32_bf16 v[90:93], v[106:109], v[178:181], v[90:93]
	v_mfma_f32_16x16x32_bf16 v[122:125], v[26:29], v[196:199], v[122:125]
	v_mfma_f32_16x16x32_bf16 v[82:85], v[106:109], v[196:199], v[82:85]
	v_mfma_f32_16x16x32_bf16 v[146:149], v[26:29], v[204:207], v[146:149]
	v_mfma_f32_16x16x32_bf16 v[110:113], v[106:109], v[204:207], v[110:113]
	s_setprio 0
	s_setprio 1
	v_mfma_f32_16x16x32_bf16 v[134:137], v[150:153], v[166:169], v[134:137]
	v_mfma_f32_16x16x32_bf16 v[94:97], v[158:161], v[166:169], v[94:97]
	v_mfma_f32_16x16x32_bf16 v[126:129], v[150:153], v[174:177], v[126:129]
	v_mfma_f32_16x16x32_bf16 v[86:89], v[158:161], v[174:177], v[86:89]
	v_mfma_f32_16x16x32_bf16 v[118:121], v[150:153], v[182:185], v[118:121]
	v_mfma_f32_16x16x32_bf16 v[78:81], v[158:161], v[182:185], v[78:81]
	v_mfma_f32_16x16x32_bf16 v[142:145], v[150:153], v[200:203], v[142:145]
	v_mfma_f32_16x16x32_bf16 v[114:117], v[158:161], v[200:203], v[114:117]
	v_mfma_f32_16x16x32_bf16 v[134:137], v[154:157], v[170:173], v[134:137]
	v_mfma_f32_16x16x32_bf16 v[94:97], v[162:165], v[170:173], v[94:97]
	v_mfma_f32_16x16x32_bf16 v[126:129], v[154:157], v[178:181], v[126:129]
	v_mfma_f32_16x16x32_bf16 v[86:89], v[162:165], v[178:181], v[86:89]
	v_mfma_f32_16x16x32_bf16 v[118:121], v[154:157], v[196:199], v[118:121]
	v_mfma_f32_16x16x32_bf16 v[78:81], v[162:165], v[196:199], v[78:81]
	v_mfma_f32_16x16x32_bf16 v[142:145], v[154:157], v[204:207], v[142:145]
	v_mfma_f32_16x16x32_bf16 v[114:117], v[162:165], v[204:207], v[114:117]
	s_setprio 0
	s_barrier
	s_add_i32 s24, s63, s1
	s_mov_b32 m0, s24
	s_nop 0
	global_load_lds_dwordx4 v0, s[8:9]
	s_add_i32 m0, s24, 0x2000
	s_add_u32 s24, s8, 0x40000
	s_addc_u32 s25, s9, 0
	s_add_i32 s3, s3, s1
	global_load_lds_dwordx4 v14, s[8:9]
	s_mov_b32 m0, s3
	s_nop 0
	global_load_lds_dwordx4 v0, s[24:25]
	s_add_i32 m0, s3, 0x2000
	s_nop 0
	global_load_lds_dwordx4 v14, s[24:25]
	s_mov_b32 m0, s54
	s_nop 0
	global_load_lds_dwordx4 v190, s[10:11]
	s_mov_b32 m0, s55
	s_nop 0
	global_load_lds_dwordx4 v188, s[10:11]
	ds_read_b128 v[166:169], v247 offset:16384
	ds_read_b128 v[170:173], v247 offset:17408
	ds_read_b128 v[174:177], v247 offset:18432
	ds_read_b128 v[178:181], v247 offset:19456
	ds_read_b128 v[182:185], v247 offset:20480
	ds_read_b128 v[196:199], v247 offset:21504
	ds_read_b128 v[200:203], v247 offset:22528
	ds_read_b128 v[204:207], v247 offset:23552
	s_waitcnt vmcnt(8)
	s_waitcnt lgkmcnt(0)
	s_barrier
	s_setprio 1
	s_waitcnt lgkmcnt(0)
	v_mfma_f32_16x16x32_bf16 v[74:77], v[22:25], v[166:169], v[74:77]
	v_mfma_f32_16x16x32_bf16 v[70:73], v[102:105], v[166:169], v[70:73]
	v_mfma_f32_16x16x32_bf16 v[66:69], v[22:25], v[174:177], v[66:69]
	v_mfma_f32_16x16x32_bf16 v[18:21], v[102:105], v[174:177], v[18:21]
	v_mfma_f32_16x16x32_bf16 v[54:57], v[22:25], v[182:185], v[54:57]
	v_mfma_f32_16x16x32_bf16 v[6:9], v[102:105], v[182:185], v[6:9]
	v_mfma_f32_16x16x32_bf16 v[22:25], v[22:25], v[200:203], v[42:45]
	v_mfma_f32_16x16x32_bf16 v[74:77], v[26:29], v[170:173], v[74:77]
	v_mfma_f32_16x16x32_bf16 v[70:73], v[106:109], v[170:173], v[70:73]
	v_mfma_f32_16x16x32_bf16 v[66:69], v[26:29], v[178:181], v[66:69]
	v_mfma_f32_16x16x32_bf16 v[18:21], v[106:109], v[178:181], v[18:21]
	v_mfma_f32_16x16x32_bf16 v[54:57], v[26:29], v[196:199], v[54:57]
	v_mfma_f32_16x16x32_bf16 v[6:9], v[106:109], v[196:199], v[6:9]
	v_mfma_f32_16x16x32_bf16 v[22:25], v[26:29], v[204:207], v[22:25]
	v_mfma_f32_16x16x32_bf16 v[26:29], v[102:105], v[200:203], v[30:33]
	v_mfma_f32_16x16x32_bf16 v[26:29], v[106:109], v[204:207], v[26:29]
	s_setprio 0
	s_setprio 1
	v_mfma_f32_16x16x32_bf16 v[30:33], v[150:153], v[166:169], v[62:65]
	v_mfma_f32_16x16x32_bf16 v[62:65], v[154:157], v[170:173], v[30:33]
	v_mfma_f32_16x16x32_bf16 v[30:33], v[158:161], v[166:169], v[58:61]
	v_mfma_f32_16x16x32_bf16 v[58:61], v[162:165], v[170:173], v[30:33]
	v_mfma_f32_16x16x32_bf16 v[30:33], v[150:153], v[174:177], v[50:53]
	v_mfma_f32_16x16x32_bf16 v[50:53], v[154:157], v[178:181], v[30:33]
	v_mfma_f32_16x16x32_bf16 v[30:33], v[150:153], v[182:185], v[46:49]
	v_mfma_f32_16x16x32_bf16 v[46:49], v[154:157], v[196:199], v[30:33]
	v_mfma_f32_16x16x32_bf16 v[30:33], v[150:153], v[200:203], v[38:41]
	v_mfma_f32_16x16x32_bf16 v[10:13], v[158:161], v[174:177], v[10:13]
	v_mfma_f32_16x16x32_bf16 v[2:5], v[158:161], v[182:185], v[2:5]
	v_mfma_f32_16x16x32_bf16 v[38:41], v[154:157], v[204:207], v[30:33]
	v_mfma_f32_16x16x32_bf16 v[30:33], v[158:161], v[200:203], v[34:37]
	v_mfma_f32_16x16x32_bf16 v[10:13], v[162:165], v[178:181], v[10:13]
	v_mfma_f32_16x16x32_bf16 v[2:5], v[162:165], v[196:199], v[2:5]
	v_mfma_f32_16x16x32_bf16 v[34:37], v[162:165], v[204:207], v[30:33]
	s_setprio 0
	s_barrier
	s_add_i32 s3, 0, 0x18000
	s_add_i32 s24, 0, 0x1c000
	s_add_u32 s10, s10, 0x40000
	s_addc_u32 s11, s11, 0
	s_mov_b32 m0, s74
	s_nop 0
	global_load_lds_dwordx4 v190, s[10:11]
	s_mov_b32 m0, s75
	s_nop 0
	global_load_lds_dwordx4 v188, s[10:11]
	v_add_u32_e32 v106, s3, v17
	v_add_u32_e32 v162, s24, v17
	ds_read_b128 v[30:33], v106
	ds_read_b128 v[42:45], v106 offset:1024
	ds_read_b128 v[102:105], v106 offset:2048
	ds_read_b128 v[106:109], v106 offset:3072
	ds_read_b128 v[150:153], v162
	ds_read_b128 v[154:157], v162 offset:1024
	ds_read_b128 v[158:161], v162 offset:2048
	ds_read_b128 v[162:165], v162 offset:3072
	ds_read_b128 v[166:169], v247 offset:32768
	ds_read_b128 v[170:173], v247 offset:33792
	ds_read_b128 v[174:177], v247 offset:34816
	ds_read_b128 v[178:181], v247 offset:35840
	ds_read_b128 v[182:185], v247 offset:36864
	ds_read_b128 v[196:199], v247 offset:37888
	ds_read_b128 v[200:203], v247 offset:38912
	ds_read_b128 v[204:207], v247 offset:39936
	s_waitcnt vmcnt(8)
	s_waitcnt lgkmcnt(0)
	s_barrier
	s_setprio 1
	s_waitcnt lgkmcnt(0)
	v_mfma_f32_16x16x32_bf16 v[138:141], v[30:33], v[166:169], v[138:141]
	v_mfma_f32_16x16x32_bf16 v[98:101], v[102:105], v[166:169], v[98:101]
	v_mfma_f32_16x16x32_bf16 v[130:133], v[30:33], v[174:177], v[130:133]
	v_mfma_f32_16x16x32_bf16 v[90:93], v[102:105], v[174:177], v[90:93]
	v_mfma_f32_16x16x32_bf16 v[122:125], v[30:33], v[182:185], v[122:125]
	v_mfma_f32_16x16x32_bf16 v[82:85], v[102:105], v[182:185], v[82:85]
	v_mfma_f32_16x16x32_bf16 v[146:149], v[30:33], v[200:203], v[146:149]
	v_mfma_f32_16x16x32_bf16 v[110:113], v[102:105], v[200:203], v[110:113]
	v_mfma_f32_16x16x32_bf16 v[138:141], v[42:45], v[170:173], v[138:141]
	v_mfma_f32_16x16x32_bf16 v[98:101], v[106:109], v[170:173], v[98:101]
	v_mfma_f32_16x16x32_bf16 v[130:133], v[42:45], v[178:181], v[130:133]
	v_mfma_f32_16x16x32_bf16 v[90:93], v[106:109], v[178:181], v[90:93]
	v_mfma_f32_16x16x32_bf16 v[122:125], v[42:45], v[196:199], v[122:125]
	v_mfma_f32_16x16x32_bf16 v[82:85], v[106:109], v[196:199], v[82:85]
	v_mfma_f32_16x16x32_bf16 v[146:149], v[42:45], v[204:207], v[146:149]
	v_mfma_f32_16x16x32_bf16 v[110:113], v[106:109], v[204:207], v[110:113]
	s_setprio 0
	s_setprio 1
	v_mfma_f32_16x16x32_bf16 v[134:137], v[150:153], v[166:169], v[134:137]
	v_mfma_f32_16x16x32_bf16 v[94:97], v[158:161], v[166:169], v[94:97]
	v_mfma_f32_16x16x32_bf16 v[126:129], v[150:153], v[174:177], v[126:129]
	v_mfma_f32_16x16x32_bf16 v[86:89], v[158:161], v[174:177], v[86:89]
	v_mfma_f32_16x16x32_bf16 v[118:121], v[150:153], v[182:185], v[118:121]
	v_mfma_f32_16x16x32_bf16 v[78:81], v[158:161], v[182:185], v[78:81]
	v_mfma_f32_16x16x32_bf16 v[142:145], v[150:153], v[200:203], v[142:145]
	v_mfma_f32_16x16x32_bf16 v[114:117], v[158:161], v[200:203], v[114:117]
	v_mfma_f32_16x16x32_bf16 v[134:137], v[154:157], v[170:173], v[134:137]
	v_mfma_f32_16x16x32_bf16 v[94:97], v[162:165], v[170:173], v[94:97]
	v_mfma_f32_16x16x32_bf16 v[126:129], v[154:157], v[178:181], v[126:129]
	v_mfma_f32_16x16x32_bf16 v[86:89], v[162:165], v[178:181], v[86:89]
	v_mfma_f32_16x16x32_bf16 v[118:121], v[154:157], v[196:199], v[118:121]
	v_mfma_f32_16x16x32_bf16 v[78:81], v[162:165], v[196:199], v[78:81]
	v_mfma_f32_16x16x32_bf16 v[142:145], v[154:157], v[204:207], v[142:145]
	v_mfma_f32_16x16x32_bf16 v[114:117], v[162:165], v[204:207], v[114:117]
	s_setprio 0
	s_barrier
	s_add_i32 s3, s3, s1
	s_mov_b32 m0, s3
	s_nop 0
	s_add_u32 s98, s8, s92
	s_addc_u32 s99, s9, s93
	global_load_lds_dwordx4 v0, s[98:99]
	s_add_i32 m0, s3, 0x2000
	s_add_u32 s8, s8, 0x40080
	s_addc_u32 s9, s9, 0
	s_add_i32 s3, s24, s1
	global_load_lds_dwordx4 v14, s[98:99]
	s_mov_b32 m0, s3
	s_nop 0
	global_load_lds_dwordx4 v0, s[8:9]
	s_add_i32 m0, s3, 0x2000
	s_nop 0
	global_load_lds_dwordx4 v14, s[8:9]
	s_mov_b32 m0, s57
	s_nop 0
	s_add_u32 s98, s10, s92
	s_addc_u32 s99, s11, s93
	s_add_u32 s98, s98, 0xfffc0000
	s_addc_u32 s99, s99, -1
	global_load_lds_dwordx4 v190, s[98:99]
	s_mov_b32 m0, s58
	s_nop 0
	global_load_lds_dwordx4 v188, s[98:99]
	ds_read_b128 v[166:169], v247 offset:49152
	ds_read_b128 v[170:173], v247 offset:50176
	ds_read_b128 v[174:177], v247 offset:51200
	ds_read_b128 v[178:181], v247 offset:52224
	ds_read_b128 v[182:185], v247 offset:53248
	ds_read_b128 v[196:199], v247 offset:54272
	ds_read_b128 v[200:203], v247 offset:55296
	ds_read_b128 v[204:207], v247 offset:56320
	s_waitcnt vmcnt(8)
	s_waitcnt lgkmcnt(0)
	s_barrier
	s_setprio 1
	s_waitcnt lgkmcnt(0)
	v_mfma_f32_16x16x32_bf16 v[74:77], v[30:33], v[166:169], v[74:77]
	v_mfma_f32_16x16x32_bf16 v[66:69], v[30:33], v[174:177], v[66:69]
	v_mfma_f32_16x16x32_bf16 v[54:57], v[30:33], v[182:185], v[54:57]
	v_mfma_f32_16x16x32_bf16 v[22:25], v[30:33], v[200:203], v[22:25]
	v_mfma_f32_16x16x32_bf16 v[74:77], v[42:45], v[170:173], v[74:77]
	v_mfma_f32_16x16x32_bf16 v[70:73], v[102:105], v[166:169], v[70:73]
	v_mfma_f32_16x16x32_bf16 v[66:69], v[42:45], v[178:181], v[66:69]
	v_mfma_f32_16x16x32_bf16 v[18:21], v[102:105], v[174:177], v[18:21]
	v_mfma_f32_16x16x32_bf16 v[54:57], v[42:45], v[196:199], v[54:57]
	v_mfma_f32_16x16x32_bf16 v[6:9], v[102:105], v[182:185], v[6:9]
	v_mfma_f32_16x16x32_bf16 v[42:45], v[42:45], v[204:207], v[22:25]
	v_mfma_f32_16x16x32_bf16 v[22:25], v[102:105], v[200:203], v[26:29]
	v_mfma_f32_16x16x32_bf16 v[70:73], v[106:109], v[170:173], v[70:73]
	v_mfma_f32_16x16x32_bf16 v[18:21], v[106:109], v[178:181], v[18:21]
	v_mfma_f32_16x16x32_bf16 v[6:9], v[106:109], v[196:199], v[6:9]
	v_mfma_f32_16x16x32_bf16 v[30:33], v[106:109], v[204:207], v[22:25]
	s_setprio 0
	s_setprio 1
	v_mfma_f32_16x16x32_bf16 v[22:25], v[150:153], v[166:169], v[62:65]
	v_mfma_f32_16x16x32_bf16 v[62:65], v[154:157], v[170:173], v[22:25]
	v_mfma_f32_16x16x32_bf16 v[22:25], v[158:161], v[166:169], v[58:61]
	v_mfma_f32_16x16x32_bf16 v[58:61], v[162:165], v[170:173], v[22:25]
	v_mfma_f32_16x16x32_bf16 v[22:25], v[150:153], v[174:177], v[50:53]
	v_mfma_f32_16x16x32_bf16 v[50:53], v[154:157], v[178:181], v[22:25]
	v_mfma_f32_16x16x32_bf16 v[22:25], v[150:153], v[182:185], v[46:49]
	v_mfma_f32_16x16x32_bf16 v[46:49], v[154:157], v[196:199], v[22:25]
	v_mfma_f32_16x16x32_bf16 v[22:25], v[150:153], v[200:203], v[38:41]
	v_mfma_f32_16x16x32_bf16 v[10:13], v[158:161], v[174:177], v[10:13]
	v_mfma_f32_16x16x32_bf16 v[2:5], v[158:161], v[182:185], v[2:5]
	v_mfma_f32_16x16x32_bf16 v[38:41], v[154:157], v[204:207], v[22:25]
	v_mfma_f32_16x16x32_bf16 v[22:25], v[158:161], v[200:203], v[34:37]
	v_mfma_f32_16x16x32_bf16 v[10:13], v[162:165], v[178:181], v[10:13]
	v_mfma_f32_16x16x32_bf16 v[2:5], v[162:165], v[196:199], v[2:5]
	v_mfma_f32_16x16x32_bf16 v[34:37], v[162:165], v[204:207], v[22:25]
	s_setprio 0
	s_barrier
	s_add_i32 s21, s21, 2
	s_add_u32 s6, s6, 0x100
	s_addc_u32 s7, s7, 0
	s_add_u32 s5, s5, 0x100
	s_addc_u32 s20, s20, 0
	s_cmp_gt_u32 s21, 13
	s_cbranch_scc0 .LBB0_142
	v_readlane_b32 s2, v255, 51
	v_readlane_b32 s3, v255, 52
	s_and_b64 vcc, exec, s[2:3]
	s_cbranch_vccz .LBB0_145
	s_barrier

.LBB0_192:
	s_add_u32 s3, s6, 0xfffc0080
	s_addc_u32 s8, s7, -1
	s_cmp_eq_u32 vcc_lo, 12
	s_cselect_b32 s37, s38, s8
	s_cselect_b32 s36, s39, s3
	s_cselect_b32 s9, s2, s84
	s_cselect_b32 s8, s43, s45
	s_add_i32 s3, 0, 0x14000
	s_add_i32 m0, s50, 0xc000
	s_nop 0
	global_load_lds_dwordx4 v182, s[6:7]
	s_add_i32 m0, s50, 0xe000
	s_nop 0
	global_load_lds_dwordx4 v184, s[6:7]
	v_add_u32_e32 v70, s63, v17
	v_add_u32_e32 v162, s3, v17
	ds_read_b128 v[54:57], v70
	ds_read_b128 v[58:61], v70 offset:1024
	ds_read_b128 v[62:65], v70 offset:2048
	ds_read_b128 v[70:73], v70 offset:3072
	ds_read_b128 v[150:153], v162
	ds_read_b128 v[154:157], v162 offset:1024
	ds_read_b128 v[158:161], v162 offset:2048
	ds_read_b128 v[162:165], v162 offset:3072
	ds_read_b128 v[166:169], v224
	ds_read_b128 v[170:173], v224 offset:1024
	ds_read_b128 v[174:177], v224 offset:2048
	ds_read_b128 v[178:181], v224 offset:3072
	ds_read_b128 v[186:189], v224 offset:4096
	ds_read_b128 v[190:193], v224 offset:5120
	ds_read_b128 v[194:197], v224 offset:6144
	ds_read_b128 v[198:201], v224 offset:7168
	s_waitcnt vmcnt(8)
	s_waitcnt lgkmcnt(0)
	s_barrier
	s_setprio 1
	s_waitcnt lgkmcnt(0)
	v_mfma_f32_16x16x32_bf16 v[146:149], v[54:57], v[166:169], v[146:149]
	v_mfma_f32_16x16x32_bf16 v[142:145], v[62:65], v[166:169], v[142:145]
	v_mfma_f32_16x16x32_bf16 v[130:133], v[54:57], v[174:177], v[130:133]
	v_mfma_f32_16x16x32_bf16 v[126:129], v[62:65], v[174:177], v[126:129]
	v_mfma_f32_16x16x32_bf16 v[114:117], v[54:57], v[186:189], v[114:117]
	v_mfma_f32_16x16x32_bf16 v[110:113], v[62:65], v[186:189], v[110:113]
	v_mfma_f32_16x16x32_bf16 v[98:101], v[54:57], v[194:197], v[98:101]
	v_mfma_f32_16x16x32_bf16 v[94:97], v[62:65], v[194:197], v[94:97]
	v_mfma_f32_16x16x32_bf16 v[146:149], v[58:61], v[170:173], v[146:149]
	v_mfma_f32_16x16x32_bf16 v[142:145], v[70:73], v[170:173], v[142:145]
	v_mfma_f32_16x16x32_bf16 v[130:133], v[58:61], v[178:181], v[130:133]
	v_mfma_f32_16x16x32_bf16 v[126:129], v[70:73], v[178:181], v[126:129]
	v_mfma_f32_16x16x32_bf16 v[114:117], v[58:61], v[190:193], v[114:117]
	v_mfma_f32_16x16x32_bf16 v[110:113], v[70:73], v[190:193], v[110:113]
	v_mfma_f32_16x16x32_bf16 v[98:101], v[58:61], v[198:201], v[98:101]
	v_mfma_f32_16x16x32_bf16 v[94:97], v[70:73], v[198:201], v[94:97]
	s_setprio 0
	s_setprio 1
	v_mfma_f32_16x16x32_bf16 v[138:141], v[150:153], v[166:169], v[138:141]
	v_mfma_f32_16x16x32_bf16 v[134:137], v[158:161], v[166:169], v[134:137]
	v_mfma_f32_16x16x32_bf16 v[122:125], v[150:153], v[174:177], v[122:125]
	v_mfma_f32_16x16x32_bf16 v[118:121], v[158:161], v[174:177], v[118:121]
	v_mfma_f32_16x16x32_bf16 v[106:109], v[150:153], v[186:189], v[106:109]
	v_mfma_f32_16x16x32_bf16 v[102:105], v[158:161], v[186:189], v[102:105]
	v_mfma_f32_16x16x32_bf16 v[90:93], v[150:153], v[194:197], v[90:93]
	v_mfma_f32_16x16x32_bf16 v[86:89], v[158:161], v[194:197], v[86:89]
	v_mfma_f32_16x16x32_bf16 v[138:141], v[154:157], v[170:173], v[138:141]
	v_mfma_f32_16x16x32_bf16 v[134:137], v[162:165], v[170:173], v[134:137]
	v_mfma_f32_16x16x32_bf16 v[122:125], v[154:157], v[178:181], v[122:125]
	v_mfma_f32_16x16x32_bf16 v[118:121], v[162:165], v[178:181], v[118:121]
	v_mfma_f32_16x16x32_bf16 v[106:109], v[154:157], v[190:193], v[106:109]
	v_mfma_f32_16x16x32_bf16 v[102:105], v[162:165], v[190:193], v[102:105]
	v_mfma_f32_16x16x32_bf16 v[90:93], v[154:157], v[198:201], v[90:93]
	v_mfma_f32_16x16x32_bf16 v[86:89], v[162:165], v[198:201], v[86:89]
	s_setprio 0
	s_barrier
	s_add_i32 s24, s63, s41
	s_mov_b32 m0, s24
	s_nop 0
	global_load_lds_dwordx4 v0, s[8:9]
	s_add_i32 m0, s24, 0x2000
	s_add_u32 s24, s8, 0x40000
	s_addc_u32 s25, s9, 0
	s_add_i32 s3, s3, s41
	global_load_lds_dwordx4 v14, s[8:9]
	s_mov_b32 m0, s3
	s_nop 0
	global_load_lds_dwordx4 v0, s[24:25]
	s_add_i32 m0, s3, 0x2000
	s_nop 0
	global_load_lds_dwordx4 v14, s[24:25]
	s_mov_b32 m0, s50
	s_nop 0
	global_load_lds_dwordx4 v0, s[36:37]
	s_mov_b32 m0, s51
	s_nop 0
	global_load_lds_dwordx4 v14, s[36:37]
	ds_read_b128 v[166:169], v224 offset:16384
	ds_read_b128 v[170:173], v224 offset:17408
	ds_read_b128 v[174:177], v224 offset:18432
	ds_read_b128 v[178:181], v224 offset:19456
	ds_read_b128 v[186:189], v224 offset:20480
	ds_read_b128 v[190:193], v224 offset:21504
	ds_read_b128 v[194:197], v224 offset:22528
	ds_read_b128 v[198:201], v224 offset:23552
	s_waitcnt vmcnt(8)
	s_waitcnt lgkmcnt(0)
	s_barrier
	s_setprio 1
	s_waitcnt lgkmcnt(0)
	v_mfma_f32_16x16x32_bf16 v[82:85], v[54:57], v[166:169], v[82:85]
	v_mfma_f32_16x16x32_bf16 v[78:81], v[62:65], v[166:169], v[78:81]
	v_mfma_f32_16x16x32_bf16 v[50:53], v[54:57], v[174:177], v[50:53]
	v_mfma_f32_16x16x32_bf16 v[46:49], v[62:65], v[174:177], v[46:49]
	v_mfma_f32_16x16x32_bf16 v[34:37], v[54:57], v[186:189], v[34:37]
	v_mfma_f32_16x16x32_bf16 v[30:33], v[62:65], v[186:189], v[30:33]
	v_mfma_f32_16x16x32_bf16 v[18:21], v[54:57], v[194:197], v[18:21]
	v_mfma_f32_16x16x32_bf16 v[10:13], v[62:65], v[194:197], v[10:13]
	v_mfma_f32_16x16x32_bf16 v[82:85], v[58:61], v[170:173], v[82:85]
	v_mfma_f32_16x16x32_bf16 v[78:81], v[70:73], v[170:173], v[78:81]
	v_mfma_f32_16x16x32_bf16 v[50:53], v[58:61], v[178:181], v[50:53]
	v_mfma_f32_16x16x32_bf16 v[46:49], v[70:73], v[178:181], v[46:49]
	v_mfma_f32_16x16x32_bf16 v[34:37], v[58:61], v[190:193], v[34:37]
	v_mfma_f32_16x16x32_bf16 v[30:33], v[70:73], v[190:193], v[30:33]
	v_mfma_f32_16x16x32_bf16 v[18:21], v[58:61], v[198:201], v[18:21]
	v_mfma_f32_16x16x32_bf16 v[10:13], v[70:73], v[198:201], v[10:13]
	s_setprio 0
	s_setprio 1
	v_mfma_f32_16x16x32_bf16 v[42:45], v[150:153], v[174:177], v[42:45]
	v_mfma_f32_16x16x32_bf16 v[38:41], v[158:161], v[174:177], v[38:41]
	v_mfma_f32_16x16x32_bf16 v[26:29], v[150:153], v[186:189], v[26:29]
	v_mfma_f32_16x16x32_bf16 v[22:25], v[158:161], v[186:189], v[22:25]
	v_mfma_f32_16x16x32_bf16 v[6:9], v[150:153], v[194:197], v[6:9]
	v_mfma_f32_16x16x32_bf16 v[2:5], v[158:161], v[194:197], v[2:5]
	v_mfma_f32_16x16x32_bf16 v[54:57], v[150:153], v[166:169], v[74:77]
	v_mfma_f32_16x16x32_bf16 v[58:61], v[158:161], v[166:169], v[66:69]
	v_mfma_f32_16x16x32_bf16 v[42:45], v[154:157], v[178:181], v[42:45]
	v_mfma_f32_16x16x32_bf16 v[38:41], v[162:165], v[178:181], v[38:41]
	v_mfma_f32_16x16x32_bf16 v[26:29], v[154:157], v[190:193], v[26:29]
	v_mfma_f32_16x16x32_bf16 v[22:25], v[162:165], v[190:193], v[22:25]
	v_mfma_f32_16x16x32_bf16 v[6:9], v[154:157], v[198:201], v[6:9]
	v_mfma_f32_16x16x32_bf16 v[2:5], v[162:165], v[198:201], v[2:5]
	v_mfma_f32_16x16x32_bf16 v[54:57], v[154:157], v[170:173], v[54:57]
	v_mfma_f32_16x16x32_bf16 v[58:61], v[162:165], v[170:173], v[58:61]
	s_setprio 0
	s_barrier
	s_add_i32 s3, 0, 0x18000
	s_add_i32 s26, 0, 0x1c000
	s_add_u32 s24, s36, 0x40000
	s_addc_u32 s25, s37, 0
	s_mov_b32 m0, s52
	s_nop 0
	global_load_lds_dwordx4 v0, s[24:25]
	s_mov_b32 m0, s53
	s_nop 0
	global_load_lds_dwordx4 v14, s[24:25]
	v_add_u32_e32 v74, s3, v17
	v_add_u32_e32 v162, s26, v17
	ds_read_b128 v[62:65], v74
	ds_read_b128 v[66:69], v74 offset:1024
	ds_read_b128 v[70:73], v74 offset:2048
	ds_read_b128 v[74:77], v74 offset:3072
	ds_read_b128 v[150:153], v162
	ds_read_b128 v[154:157], v162 offset:1024
	ds_read_b128 v[158:161], v162 offset:2048
	ds_read_b128 v[162:165], v162 offset:3072
	ds_read_b128 v[166:169], v224 offset:32768
	ds_read_b128 v[170:173], v224 offset:33792
	ds_read_b128 v[174:177], v224 offset:34816
	ds_read_b128 v[178:181], v224 offset:35840
	ds_read_b128 v[186:189], v224 offset:36864
	ds_read_b128 v[190:193], v224 offset:37888
	ds_read_b128 v[194:197], v224 offset:38912
	ds_read_b128 v[198:201], v224 offset:39936
	s_waitcnt vmcnt(8)
	s_waitcnt lgkmcnt(0)
	s_barrier
	s_setprio 1
	s_waitcnt lgkmcnt(0)
	v_mfma_f32_16x16x32_bf16 v[146:149], v[62:65], v[166:169], v[146:149]
	v_mfma_f32_16x16x32_bf16 v[142:145], v[70:73], v[166:169], v[142:145]
	v_mfma_f32_16x16x32_bf16 v[130:133], v[62:65], v[174:177], v[130:133]
	v_mfma_f32_16x16x32_bf16 v[126:129], v[70:73], v[174:177], v[126:129]
	v_mfma_f32_16x16x32_bf16 v[114:117], v[62:65], v[186:189], v[114:117]
	v_mfma_f32_16x16x32_bf16 v[110:113], v[70:73], v[186:189], v[110:113]
	v_mfma_f32_16x16x32_bf16 v[98:101], v[62:65], v[194:197], v[98:101]
	v_mfma_f32_16x16x32_bf16 v[94:97], v[70:73], v[194:197], v[94:97]
	v_mfma_f32_16x16x32_bf16 v[146:149], v[66:69], v[170:173], v[146:149]
	v_mfma_f32_16x16x32_bf16 v[142:145], v[74:77], v[170:173], v[142:145]
	v_mfma_f32_16x16x32_bf16 v[130:133], v[66:69], v[178:181], v[130:133]
	v_mfma_f32_16x16x32_bf16 v[126:129], v[74:77], v[178:181], v[126:129]
	v_mfma_f32_16x16x32_bf16 v[114:117], v[66:69], v[190:193], v[114:117]
	v_mfma_f32_16x16x32_bf16 v[110:113], v[74:77], v[190:193], v[110:113]
	v_mfma_f32_16x16x32_bf16 v[98:101], v[66:69], v[198:201], v[98:101]
	v_mfma_f32_16x16x32_bf16 v[94:97], v[74:77], v[198:201], v[94:97]
	s_setprio 0
	s_setprio 1
	v_mfma_f32_16x16x32_bf16 v[138:141], v[150:153], v[166:169], v[138:141]
	v_mfma_f32_16x16x32_bf16 v[134:137], v[158:161], v[166:169], v[134:137]
	v_mfma_f32_16x16x32_bf16 v[122:125], v[150:153], v[174:177], v[122:125]
	v_mfma_f32_16x16x32_bf16 v[118:121], v[158:161], v[174:177], v[118:121]
	v_mfma_f32_16x16x32_bf16 v[106:109], v[150:153], v[186:189], v[106:109]
	v_mfma_f32_16x16x32_bf16 v[102:105], v[158:161], v[186:189], v[102:105]
	v_mfma_f32_16x16x32_bf16 v[90:93], v[150:153], v[194:197], v[90:93]
	v_mfma_f32_16x16x32_bf16 v[86:89], v[158:161], v[194:197], v[86:89]
	v_mfma_f32_16x16x32_bf16 v[138:141], v[154:157], v[170:173], v[138:141]
	v_mfma_f32_16x16x32_bf16 v[134:137], v[162:165], v[170:173], v[134:137]
	v_mfma_f32_16x16x32_bf16 v[122:125], v[154:157], v[178:181], v[122:125]
	v_mfma_f32_16x16x32_bf16 v[118:121], v[162:165], v[178:181], v[118:121]
	v_mfma_f32_16x16x32_bf16 v[106:109], v[154:157], v[190:193], v[106:109]
	v_mfma_f32_16x16x32_bf16 v[102:105], v[162:165], v[190:193], v[102:105]
	v_mfma_f32_16x16x32_bf16 v[90:93], v[154:157], v[198:201], v[90:93]
	v_mfma_f32_16x16x32_bf16 v[86:89], v[162:165], v[198:201], v[86:89]
	s_setprio 0
	s_barrier
	s_add_i32 s3, s3, s41
	s_mov_b32 m0, s3
	s_nop 0
	s_add_u32 s98, s8, s92
	s_addc_u32 s99, s9, s93
	global_load_lds_dwordx4 v0, s[98:99]
	s_add_i32 m0, s3, 0x2000
	s_add_u32 s8, s8, 0x40080
	s_addc_u32 s9, s9, 0
	s_add_i32 s3, s26, s41
	global_load_lds_dwordx4 v14, s[98:99]
	s_mov_b32 m0, s3
	s_nop 0
	global_load_lds_dwordx4 v0, s[8:9]
	s_add_i32 m0, s3, 0x2000
	s_nop 0
	global_load_lds_dwordx4 v14, s[8:9]
	s_mov_b32 m0, s59
	s_nop 0
	s_add_u32 s98, s36, s92
	s_addc_u32 s99, s37, s93
	global_load_lds_dwordx4 v0, s[98:99]
	s_mov_b32 m0, s74
	s_nop 0
	global_load_lds_dwordx4 v14, s[98:99]
	ds_read_b128 v[166:169], v224 offset:49152
	ds_read_b128 v[170:173], v224 offset:50176
	ds_read_b128 v[174:177], v224 offset:51200
	ds_read_b128 v[178:181], v224 offset:52224
	ds_read_b128 v[186:189], v224 offset:53248
	ds_read_b128 v[190:193], v224 offset:54272
	ds_read_b128 v[194:197], v224 offset:55296
	ds_read_b128 v[198:201], v224 offset:56320
	s_waitcnt vmcnt(8)
	s_waitcnt lgkmcnt(0)
	s_barrier
	s_setprio 1
	s_waitcnt lgkmcnt(0)
	v_mfma_f32_16x16x32_bf16 v[82:85], v[62:65], v[166:169], v[82:85]
	v_mfma_f32_16x16x32_bf16 v[78:81], v[70:73], v[166:169], v[78:81]
	v_mfma_f32_16x16x32_bf16 v[50:53], v[62:65], v[174:177], v[50:53]
	v_mfma_f32_16x16x32_bf16 v[46:49], v[70:73], v[174:177], v[46:49]
	v_mfma_f32_16x16x32_bf16 v[34:37], v[62:65], v[186:189], v[34:37]
	v_mfma_f32_16x16x32_bf16 v[30:33], v[70:73], v[186:189], v[30:33]
	v_mfma_f32_16x16x32_bf16 v[18:21], v[62:65], v[194:197], v[18:21]
	v_mfma_f32_16x16x32_bf16 v[10:13], v[70:73], v[194:197], v[10:13]
	v_mfma_f32_16x16x32_bf16 v[82:85], v[66:69], v[170:173], v[82:85]
	v_mfma_f32_16x16x32_bf16 v[78:81], v[74:77], v[170:173], v[78:81]
	v_mfma_f32_16x16x32_bf16 v[50:53], v[66:69], v[178:181], v[50:53]
	v_mfma_f32_16x16x32_bf16 v[46:49], v[74:77], v[178:181], v[46:49]
	v_mfma_f32_16x16x32_bf16 v[34:37], v[66:69], v[190:193], v[34:37]
	v_mfma_f32_16x16x32_bf16 v[30:33], v[74:77], v[190:193], v[30:33]
	v_mfma_f32_16x16x32_bf16 v[18:21], v[66:69], v[198:201], v[18:21]
	v_mfma_f32_16x16x32_bf16 v[10:13], v[74:77], v[198:201], v[10:13]
	s_setprio 0
	s_setprio 1
	v_mfma_f32_16x16x32_bf16 v[54:57], v[150:153], v[166:169], v[54:57]
	v_mfma_f32_16x16x32_bf16 v[74:77], v[154:157], v[170:173], v[54:57]
	v_mfma_f32_16x16x32_bf16 v[54:57], v[158:161], v[166:169], v[58:61]
	v_mfma_f32_16x16x32_bf16 v[42:45], v[150:153], v[174:177], v[42:45]
	v_mfma_f32_16x16x32_bf16 v[38:41], v[158:161], v[174:177], v[38:41]
	v_mfma_f32_16x16x32_bf16 v[26:29], v[150:153], v[186:189], v[26:29]
	v_mfma_f32_16x16x32_bf16 v[22:25], v[158:161], v[186:189], v[22:25]
	v_mfma_f32_16x16x32_bf16 v[6:9], v[150:153], v[194:197], v[6:9]
	v_mfma_f32_16x16x32_bf16 v[2:5], v[158:161], v[194:197], v[2:5]
	v_mfma_f32_16x16x32_bf16 v[66:69], v[162:165], v[170:173], v[54:57]
	v_mfma_f32_16x16x32_bf16 v[42:45], v[154:157], v[178:181], v[42:45]
	v_mfma_f32_16x16x32_bf16 v[38:41], v[162:165], v[178:181], v[38:41]
	v_mfma_f32_16x16x32_bf16 v[26:29], v[154:157], v[190:193], v[26:29]
	v_mfma_f32_16x16x32_bf16 v[22:25], v[162:165], v[190:193], v[22:25]
	v_mfma_f32_16x16x32_bf16 v[6:9], v[154:157], v[198:201], v[6:9]
	v_mfma_f32_16x16x32_bf16 v[2:5], v[162:165], v[198:201], v[2:5]
	s_setprio 0
	s_barrier
	s_add_i32 vcc_lo, vcc_lo, 2
	s_add_u32 s6, s6, 0x100
	s_addc_u32 s7, s7, 0
	s_add_u32 s45, s45, 0x100
	s_addc_u32 s84, s84, 0
	s_cmp_gt_u32 vcc_lo, 13
	s_cbranch_scc0 .LBB0_192
	s_and_b64 vcc, exec, s[18:19]
	s_cbranch_vccz .LBB0_195
	s_barrier

.LBB0_751:
	s_add_u32 s6, s22, 0x100
	s_addc_u32 s7, s23, 0
	s_cmp_eq_u32 s57, 40
	s_cselect_b32 s39, s17, s7
	s_cselect_b32 s38, s16, s6
	s_cselect_b32 s37, s19, s55
	s_cselect_b32 s36, s18, s2
	s_add_i32 s3, 0, 0x14000
	v_lshl_add_u64 v[198:199], s[22:23], 0, v[222:223]
	s_add_i32 m0, s42, 0xc000
	s_nop 0
	global_load_lds_dwordx4 v[198:199], off
	v_lshl_add_u64 v[198:199], s[22:23], 0, v[224:225]
	s_add_i32 m0, s42, 0xe000
	s_nop 0
	global_load_lds_dwordx4 v[198:199], off
	v_add_u32_e32 v82, s63, v17
	v_add_u32_e32 v162, s3, v17
	ds_read_b128 v[70:73], v82
	ds_read_b128 v[74:77], v82 offset:1024
	ds_read_b128 v[78:81], v82 offset:2048
	ds_read_b128 v[82:85], v82 offset:3072
	ds_read_b128 v[150:153], v162
	ds_read_b128 v[154:157], v162 offset:1024
	ds_read_b128 v[158:161], v162 offset:2048
	ds_read_b128 v[162:165], v162 offset:3072
	ds_read_b128 v[166:169], v242
	ds_read_b128 v[170:173], v242 offset:1024
	ds_read_b128 v[174:177], v242 offset:2048
	ds_read_b128 v[178:181], v242 offset:3072
	ds_read_b128 v[182:185], v242 offset:4096
	ds_read_b128 v[186:189], v242 offset:5120
	ds_read_b128 v[190:193], v242 offset:6144
	ds_read_b128 v[194:197], v242 offset:7168
	s_waitcnt vmcnt(8)
	s_waitcnt lgkmcnt(0)
	s_barrier
	s_setprio 1
	s_waitcnt lgkmcnt(0)
	v_mfma_f32_16x16x32_bf16 v[146:149], v[70:73], v[166:169], v[146:149]
	v_mfma_f32_16x16x32_bf16 v[142:145], v[78:81], v[166:169], v[142:145]
	v_mfma_f32_16x16x32_bf16 v[130:133], v[70:73], v[174:177], v[130:133]
	v_mfma_f32_16x16x32_bf16 v[126:129], v[78:81], v[174:177], v[126:129]
	v_mfma_f32_16x16x32_bf16 v[114:117], v[70:73], v[182:185], v[114:117]
	v_mfma_f32_16x16x32_bf16 v[110:113], v[78:81], v[182:185], v[110:113]
	v_mfma_f32_16x16x32_bf16 v[98:101], v[70:73], v[190:193], v[98:101]
	v_mfma_f32_16x16x32_bf16 v[94:97], v[78:81], v[190:193], v[94:97]
	v_mfma_f32_16x16x32_bf16 v[146:149], v[74:77], v[170:173], v[146:149]
	v_mfma_f32_16x16x32_bf16 v[142:145], v[82:85], v[170:173], v[142:145]
	v_mfma_f32_16x16x32_bf16 v[130:133], v[74:77], v[178:181], v[130:133]
	v_mfma_f32_16x16x32_bf16 v[126:129], v[82:85], v[178:181], v[126:129]
	v_mfma_f32_16x16x32_bf16 v[114:117], v[74:77], v[186:189], v[114:117]
	v_mfma_f32_16x16x32_bf16 v[110:113], v[82:85], v[186:189], v[110:113]
	v_mfma_f32_16x16x32_bf16 v[98:101], v[74:77], v[194:197], v[98:101]
	v_mfma_f32_16x16x32_bf16 v[94:97], v[82:85], v[194:197], v[94:97]
	s_setprio 0
	s_setprio 1
	v_mfma_f32_16x16x32_bf16 v[138:141], v[150:153], v[166:169], v[138:141]
	v_mfma_f32_16x16x32_bf16 v[134:137], v[158:161], v[166:169], v[134:137]
	v_mfma_f32_16x16x32_bf16 v[122:125], v[150:153], v[174:177], v[122:125]
	v_mfma_f32_16x16x32_bf16 v[118:121], v[158:161], v[174:177], v[118:121]
	v_mfma_f32_16x16x32_bf16 v[106:109], v[150:153], v[182:185], v[106:109]
	v_mfma_f32_16x16x32_bf16 v[102:105], v[158:161], v[182:185], v[102:105]
	v_mfma_f32_16x16x32_bf16 v[90:93], v[150:153], v[190:193], v[90:93]
	v_mfma_f32_16x16x32_bf16 v[86:89], v[158:161], v[190:193], v[86:89]
	v_mfma_f32_16x16x32_bf16 v[138:141], v[154:157], v[170:173], v[138:141]
	v_mfma_f32_16x16x32_bf16 v[134:137], v[162:165], v[170:173], v[134:137]
	v_mfma_f32_16x16x32_bf16 v[122:125], v[154:157], v[178:181], v[122:125]
	v_mfma_f32_16x16x32_bf16 v[118:121], v[162:165], v[178:181], v[118:121]
	v_mfma_f32_16x16x32_bf16 v[106:109], v[154:157], v[186:189], v[106:109]
	v_mfma_f32_16x16x32_bf16 v[102:105], v[162:165], v[186:189], v[102:105]
	v_mfma_f32_16x16x32_bf16 v[90:93], v[154:157], v[194:197], v[90:93]
	v_mfma_f32_16x16x32_bf16 v[86:89], v[162:165], v[194:197], v[86:89]
	s_setprio 0
	s_barrier
	s_add_i32 s22, s63, s41
	s_mov_b32 m0, s22
	s_nop 0
	global_load_lds_dwordx4 v0, s[36:37]
	s_add_i32 m0, s22, 0x2000
	s_add_u32 s22, s36, 0xb0000
	s_addc_u32 s23, s37, 0
	s_add_i32 s3, s3, s41
	global_load_lds_dwordx4 v14, s[36:37]
	s_mov_b32 m0, s3
	s_nop 0
	global_load_lds_dwordx4 v0, s[22:23]
	s_add_i32 m0, s3, 0x2000
	s_nop 0
	global_load_lds_dwordx4 v14, s[22:23]
	s_mov_b32 m0, s42
	s_nop 0
	global_load_lds_dwordx4 v0, s[38:39]
	s_mov_b32 m0, s43
	s_nop 0
	global_load_lds_dwordx4 v14, s[38:39]
	ds_read_b128 v[166:169], v242 offset:16384
	ds_read_b128 v[170:173], v242 offset:17408
	ds_read_b128 v[174:177], v242 offset:18432
	ds_read_b128 v[178:181], v242 offset:19456
	ds_read_b128 v[182:185], v242 offset:20480
	ds_read_b128 v[186:189], v242 offset:21504
	ds_read_b128 v[190:193], v242 offset:22528
	ds_read_b128 v[194:197], v242 offset:23552
	s_waitcnt vmcnt(8)
	s_waitcnt lgkmcnt(0)
	s_barrier
	s_setprio 1
	s_waitcnt lgkmcnt(0)
	v_mfma_f32_16x16x32_bf16 v[66:69], v[70:73], v[166:169], v[66:69]
	v_mfma_f32_16x16x32_bf16 v[62:65], v[78:81], v[166:169], v[62:65]
	v_mfma_f32_16x16x32_bf16 v[50:53], v[70:73], v[174:177], v[50:53]
	v_mfma_f32_16x16x32_bf16 v[46:49], v[78:81], v[174:177], v[46:49]
	v_mfma_f32_16x16x32_bf16 v[34:37], v[70:73], v[182:185], v[34:37]
	v_mfma_f32_16x16x32_bf16 v[30:33], v[78:81], v[182:185], v[30:33]
	v_mfma_f32_16x16x32_bf16 v[18:21], v[70:73], v[190:193], v[18:21]
	v_mfma_f32_16x16x32_bf16 v[10:13], v[78:81], v[190:193], v[10:13]
	v_mfma_f32_16x16x32_bf16 v[66:69], v[74:77], v[170:173], v[66:69]
	v_mfma_f32_16x16x32_bf16 v[62:65], v[82:85], v[170:173], v[62:65]
	v_mfma_f32_16x16x32_bf16 v[50:53], v[74:77], v[178:181], v[50:53]
	v_mfma_f32_16x16x32_bf16 v[46:49], v[82:85], v[178:181], v[46:49]
	v_mfma_f32_16x16x32_bf16 v[34:37], v[74:77], v[186:189], v[34:37]
	v_mfma_f32_16x16x32_bf16 v[30:33], v[82:85], v[186:189], v[30:33]
	v_mfma_f32_16x16x32_bf16 v[18:21], v[74:77], v[194:197], v[18:21]
	v_mfma_f32_16x16x32_bf16 v[10:13], v[82:85], v[194:197], v[10:13]
	s_setprio 0
	s_setprio 1
	v_mfma_f32_16x16x32_bf16 v[58:61], v[150:153], v[166:169], v[58:61]
	v_mfma_f32_16x16x32_bf16 v[54:57], v[158:161], v[166:169], v[54:57]
	v_mfma_f32_16x16x32_bf16 v[42:45], v[150:153], v[174:177], v[42:45]
	v_mfma_f32_16x16x32_bf16 v[38:41], v[158:161], v[174:177], v[38:41]
	v_mfma_f32_16x16x32_bf16 v[26:29], v[150:153], v[182:185], v[26:29]
	v_mfma_f32_16x16x32_bf16 v[22:25], v[158:161], v[182:185], v[22:25]
	v_mfma_f32_16x16x32_bf16 v[6:9], v[150:153], v[190:193], v[6:9]
	v_mfma_f32_16x16x32_bf16 v[2:5], v[158:161], v[190:193], v[2:5]
	v_mfma_f32_16x16x32_bf16 v[58:61], v[154:157], v[170:173], v[58:61]
	v_mfma_f32_16x16x32_bf16 v[54:57], v[162:165], v[170:173], v[54:57]
	v_mfma_f32_16x16x32_bf16 v[42:45], v[154:157], v[178:181], v[42:45]
	v_mfma_f32_16x16x32_bf16 v[38:41], v[162:165], v[178:181], v[38:41]
	v_mfma_f32_16x16x32_bf16 v[26:29], v[154:157], v[186:189], v[26:29]
	v_mfma_f32_16x16x32_bf16 v[22:25], v[162:165], v[186:189], v[22:25]
	v_mfma_f32_16x16x32_bf16 v[6:9], v[154:157], v[194:197], v[6:9]
	v_mfma_f32_16x16x32_bf16 v[2:5], v[162:165], v[194:197], v[2:5]
	s_setprio 0
	s_barrier
	s_add_i32 s3, 0, 0x18000
	s_add_i32 s24, 0, 0x1c000
	s_add_u32 s22, s38, 0xb0000
	s_addc_u32 s23, s39, 0
	s_mov_b32 m0, s44
	s_nop 0
	global_load_lds_dwordx4 v0, s[22:23]
	s_mov_b32 m0, s45
	s_nop 0
	global_load_lds_dwordx4 v14, s[22:23]
	v_add_u32_e32 v82, s3, v17
	v_add_u32_e32 v162, s24, v17
	ds_read_b128 v[70:73], v82
	ds_read_b128 v[74:77], v82 offset:1024
	ds_read_b128 v[78:81], v82 offset:2048
	ds_read_b128 v[82:85], v82 offset:3072
	ds_read_b128 v[150:153], v162
	ds_read_b128 v[154:157], v162 offset:1024
	ds_read_b128 v[158:161], v162 offset:2048
	ds_read_b128 v[162:165], v162 offset:3072
	ds_read_b128 v[166:169], v242 offset:32768
	ds_read_b128 v[170:173], v242 offset:33792
	ds_read_b128 v[174:177], v242 offset:34816
	ds_read_b128 v[178:181], v242 offset:35840
	ds_read_b128 v[182:185], v242 offset:36864
	ds_read_b128 v[186:189], v242 offset:37888
	ds_read_b128 v[190:193], v242 offset:38912
	ds_read_b128 v[194:197], v242 offset:39936
	s_waitcnt vmcnt(8)
	s_waitcnt lgkmcnt(0)
	s_barrier
	s_setprio 1
	s_waitcnt lgkmcnt(0)
	v_mfma_f32_16x16x32_bf16 v[146:149], v[70:73], v[166:169], v[146:149]
	v_mfma_f32_16x16x32_bf16 v[142:145], v[78:81], v[166:169], v[142:145]
	v_mfma_f32_16x16x32_bf16 v[130:133], v[70:73], v[174:177], v[130:133]
	v_mfma_f32_16x16x32_bf16 v[126:129], v[78:81], v[174:177], v[126:129]
	v_mfma_f32_16x16x32_bf16 v[114:117], v[70:73], v[182:185], v[114:117]
	v_mfma_f32_16x16x32_bf16 v[110:113], v[78:81], v[182:185], v[110:113]
	v_mfma_f32_16x16x32_bf16 v[98:101], v[70:73], v[190:193], v[98:101]
	v_mfma_f32_16x16x32_bf16 v[94:97], v[78:81], v[190:193], v[94:97]
	v_mfma_f32_16x16x32_bf16 v[146:149], v[74:77], v[170:173], v[146:149]
	v_mfma_f32_16x16x32_bf16 v[142:145], v[82:85], v[170:173], v[142:145]
	v_mfma_f32_16x16x32_bf16 v[130:133], v[74:77], v[178:181], v[130:133]
	v_mfma_f32_16x16x32_bf16 v[126:129], v[82:85], v[178:181], v[126:129]
	v_mfma_f32_16x16x32_bf16 v[114:117], v[74:77], v[186:189], v[114:117]
	v_mfma_f32_16x16x32_bf16 v[110:113], v[82:85], v[186:189], v[110:113]
	v_mfma_f32_16x16x32_bf16 v[98:101], v[74:77], v[194:197], v[98:101]
	v_mfma_f32_16x16x32_bf16 v[94:97], v[82:85], v[194:197], v[94:97]
	s_setprio 0
	s_setprio 1
	v_mfma_f32_16x16x32_bf16 v[138:141], v[150:153], v[166:169], v[138:141]
	v_mfma_f32_16x16x32_bf16 v[134:137], v[158:161], v[166:169], v[134:137]
	v_mfma_f32_16x16x32_bf16 v[122:125], v[150:153], v[174:177], v[122:125]
	v_mfma_f32_16x16x32_bf16 v[118:121], v[158:161], v[174:177], v[118:121]
	v_mfma_f32_16x16x32_bf16 v[106:109], v[150:153], v[182:185], v[106:109]
	v_mfma_f32_16x16x32_bf16 v[102:105], v[158:161], v[182:185], v[102:105]
	v_mfma_f32_16x16x32_bf16 v[90:93], v[150:153], v[190:193], v[90:93]
	v_mfma_f32_16x16x32_bf16 v[86:89], v[158:161], v[190:193], v[86:89]
	v_mfma_f32_16x16x32_bf16 v[138:141], v[154:157], v[170:173], v[138:141]
	v_mfma_f32_16x16x32_bf16 v[134:137], v[162:165], v[170:173], v[134:137]
	v_mfma_f32_16x16x32_bf16 v[122:125], v[154:157], v[178:181], v[122:125]
	v_mfma_f32_16x16x32_bf16 v[118:121], v[162:165], v[178:181], v[118:121]
	v_mfma_f32_16x16x32_bf16 v[106:109], v[154:157], v[186:189], v[106:109]
	v_mfma_f32_16x16x32_bf16 v[102:105], v[162:165], v[186:189], v[102:105]
	v_mfma_f32_16x16x32_bf16 v[90:93], v[154:157], v[194:197], v[90:93]
	v_mfma_f32_16x16x32_bf16 v[86:89], v[162:165], v[194:197], v[86:89]
	s_setprio 0
	s_barrier
	s_add_i32 s3, s3, s41
	s_mov_b32 m0, s3
	s_nop 0
	s_add_u32 s98, s36, s92
	s_addc_u32 s99, s37, s93
	global_load_lds_dwordx4 v0, s[98:99]
	s_add_i32 m0, s3, 0x2000
	s_add_u32 s22, s36, 0xb0080
	s_addc_u32 s23, s37, 0
	s_add_i32 s3, s24, s41
	global_load_lds_dwordx4 v14, s[98:99]
	s_mov_b32 m0, s3
	s_nop 0
	global_load_lds_dwordx4 v0, s[22:23]
	s_add_i32 m0, s3, 0x2000
	s_nop 0
	global_load_lds_dwordx4 v14, s[22:23]
	s_mov_b32 m0, s50
	s_nop 0
	s_add_u32 s98, s38, s92
	s_addc_u32 s99, s39, s93
	global_load_lds_dwordx4 v0, s[98:99]
	s_mov_b32 m0, s51
	s_nop 0
	global_load_lds_dwordx4 v14, s[98:99]
	ds_read_b128 v[166:169], v242 offset:49152
	ds_read_b128 v[170:173], v242 offset:50176
	ds_read_b128 v[174:177], v242 offset:51200
	ds_read_b128 v[178:181], v242 offset:52224
	ds_read_b128 v[182:185], v242 offset:53248
	ds_read_b128 v[186:189], v242 offset:54272
	ds_read_b128 v[190:193], v242 offset:55296
	ds_read_b128 v[194:197], v242 offset:56320
	s_waitcnt vmcnt(8)
	s_waitcnt lgkmcnt(0)
	s_barrier
	s_setprio 1
	s_waitcnt lgkmcnt(0)
	v_mfma_f32_16x16x32_bf16 v[66:69], v[70:73], v[166:169], v[66:69]
	v_mfma_f32_16x16x32_bf16 v[62:65], v[78:81], v[166:169], v[62:65]
	v_mfma_f32_16x16x32_bf16 v[50:53], v[70:73], v[174:177], v[50:53]
	v_mfma_f32_16x16x32_bf16 v[46:49], v[78:81], v[174:177], v[46:49]
	v_mfma_f32_16x16x32_bf16 v[34:37], v[70:73], v[182:185], v[34:37]
	v_mfma_f32_16x16x32_bf16 v[30:33], v[78:81], v[182:185], v[30:33]
	v_mfma_f32_16x16x32_bf16 v[18:21], v[70:73], v[190:193], v[18:21]
	v_mfma_f32_16x16x32_bf16 v[10:13], v[78:81], v[190:193], v[10:13]
	v_mfma_f32_16x16x32_bf16 v[66:69], v[74:77], v[170:173], v[66:69]
	v_mfma_f32_16x16x32_bf16 v[62:65], v[82:85], v[170:173], v[62:65]
	v_mfma_f32_16x16x32_bf16 v[50:53], v[74:77], v[178:181], v[50:53]
	v_mfma_f32_16x16x32_bf16 v[46:49], v[82:85], v[178:181], v[46:49]
	v_mfma_f32_16x16x32_bf16 v[34:37], v[74:77], v[186:189], v[34:37]
	v_mfma_f32_16x16x32_bf16 v[30:33], v[82:85], v[186:189], v[30:33]
	v_mfma_f32_16x16x32_bf16 v[18:21], v[74:77], v[194:197], v[18:21]
	v_mfma_f32_16x16x32_bf16 v[10:13], v[82:85], v[194:197], v[10:13]
	s_setprio 0
	s_setprio 1
	v_mfma_f32_16x16x32_bf16 v[58:61], v[150:153], v[166:169], v[58:61]
	v_mfma_f32_16x16x32_bf16 v[54:57], v[158:161], v[166:169], v[54:57]
	v_mfma_f32_16x16x32_bf16 v[42:45], v[150:153], v[174:177], v[42:45]
	v_mfma_f32_16x16x32_bf16 v[38:41], v[158:161], v[174:177], v[38:41]
	v_mfma_f32_16x16x32_bf16 v[26:29], v[150:153], v[182:185], v[26:29]
	v_mfma_f32_16x16x32_bf16 v[22:25], v[158:161], v[182:185], v[22:25]
	v_mfma_f32_16x16x32_bf16 v[6:9], v[150:153], v[190:193], v[6:9]
	v_mfma_f32_16x16x32_bf16 v[2:5], v[158:161], v[190:193], v[2:5]
	v_mfma_f32_16x16x32_bf16 v[58:61], v[154:157], v[170:173], v[58:61]
	v_mfma_f32_16x16x32_bf16 v[54:57], v[162:165], v[170:173], v[54:57]
	v_mfma_f32_16x16x32_bf16 v[42:45], v[154:157], v[178:181], v[42:45]
	v_mfma_f32_16x16x32_bf16 v[38:41], v[162:165], v[178:181], v[38:41]
	v_mfma_f32_16x16x32_bf16 v[26:29], v[154:157], v[186:189], v[26:29]
	v_mfma_f32_16x16x32_bf16 v[22:25], v[162:165], v[186:189], v[22:25]
	v_mfma_f32_16x16x32_bf16 v[6:9], v[154:157], v[194:197], v[6:9]
	v_mfma_f32_16x16x32_bf16 v[2:5], v[162:165], v[194:197], v[2:5]
	s_setprio 0
	s_barrier
	s_add_i32 s57, s57, 2
	s_add_u32 s2, s2, 0x100
	s_addc_u32 s55, s55, 0
	s_cmp_gt_u32 s57, 41
	s_mov_b64 s[22:23], s[6:7]
	s_cbranch_scc0 .LBB0_751
	s_and_b64 vcc, exec, s[12:13]
	s_cbranch_vccz .LBB0_754
	s_barrier

.LBB0_817:
	s_add_u32 s3, s36, 0xfffc0080
	s_addc_u32 s24, s37, -1
	s_cmp_eq_u32 s50, 12
	s_cselect_b32 s41, s17, s24
	s_cselect_b32 s40, s47, s3
	s_cselect_b32 s39, s2, s49
	s_cselect_b32 s38, s15, s48
	s_add_i32 s3, 0, 0x14000
	s_add_i32 m0, s28, 0xc000
	s_nop 0
	global_load_lds_dwordx4 v154, s[36:37]
	s_add_i32 m0, s28, 0xe000
	s_nop 0
	global_load_lds_dwordx4 v156, s[36:37]
	v_add_u32_e32 v146, s63, v17
	v_add_u32_e32 v170, s3, v17
	ds_read_b128 v[134:137], v146
	ds_read_b128 v[138:141], v146 offset:1024
	ds_read_b128 v[142:145], v146 offset:2048
	ds_read_b128 v[146:149], v146 offset:3072
	ds_read_b128 v[158:161], v170
	ds_read_b128 v[162:165], v170 offset:1024
	ds_read_b128 v[166:169], v170 offset:2048
	ds_read_b128 v[170:173], v170 offset:3072
	ds_read_b128 v[174:177], v182
	ds_read_b128 v[178:181], v182 offset:1024
	ds_read_b128 v[184:187], v182 offset:2048
	ds_read_b128 v[188:191], v182 offset:3072
	ds_read_b128 v[192:195], v182 offset:4096
	ds_read_b128 v[196:199], v182 offset:5120
	ds_read_b128 v[200:203], v182 offset:6144
	ds_read_b128 v[204:207], v182 offset:7168
	s_waitcnt vmcnt(8)
	s_waitcnt lgkmcnt(0)
	s_barrier
	s_setprio 1
	s_waitcnt lgkmcnt(0)
	v_mfma_f32_16x16x32_bf16 v[130:133], v[134:137], v[174:177], v[130:133]
	v_mfma_f32_16x16x32_bf16 v[126:129], v[142:145], v[174:177], v[126:129]
	v_mfma_f32_16x16x32_bf16 v[114:117], v[134:137], v[184:187], v[114:117]
	v_mfma_f32_16x16x32_bf16 v[110:113], v[142:145], v[184:187], v[110:113]
	v_mfma_f32_16x16x32_bf16 v[98:101], v[134:137], v[192:195], v[98:101]
	v_mfma_f32_16x16x32_bf16 v[94:97], v[142:145], v[192:195], v[94:97]
	v_mfma_f32_16x16x32_bf16 v[82:85], v[134:137], v[200:203], v[82:85]
	v_mfma_f32_16x16x32_bf16 v[78:81], v[142:145], v[200:203], v[78:81]
	v_mfma_f32_16x16x32_bf16 v[130:133], v[138:141], v[178:181], v[130:133]
	v_mfma_f32_16x16x32_bf16 v[126:129], v[146:149], v[178:181], v[126:129]
	v_mfma_f32_16x16x32_bf16 v[114:117], v[138:141], v[188:191], v[114:117]
	v_mfma_f32_16x16x32_bf16 v[110:113], v[146:149], v[188:191], v[110:113]
	v_mfma_f32_16x16x32_bf16 v[98:101], v[138:141], v[196:199], v[98:101]
	v_mfma_f32_16x16x32_bf16 v[94:97], v[146:149], v[196:199], v[94:97]
	v_mfma_f32_16x16x32_bf16 v[82:85], v[138:141], v[204:207], v[82:85]
	v_mfma_f32_16x16x32_bf16 v[78:81], v[146:149], v[204:207], v[78:81]
	s_setprio 0
	s_setprio 1
	v_mfma_f32_16x16x32_bf16 v[122:125], v[158:161], v[174:177], v[122:125]
	v_mfma_f32_16x16x32_bf16 v[118:121], v[166:169], v[174:177], v[118:121]
	v_mfma_f32_16x16x32_bf16 v[106:109], v[158:161], v[184:187], v[106:109]
	v_mfma_f32_16x16x32_bf16 v[102:105], v[166:169], v[184:187], v[102:105]
	v_mfma_f32_16x16x32_bf16 v[90:93], v[158:161], v[192:195], v[90:93]
	v_mfma_f32_16x16x32_bf16 v[86:89], v[166:169], v[192:195], v[86:89]
	v_mfma_f32_16x16x32_bf16 v[74:77], v[158:161], v[200:203], v[74:77]
	v_mfma_f32_16x16x32_bf16 v[70:73], v[166:169], v[200:203], v[70:73]
	v_mfma_f32_16x16x32_bf16 v[122:125], v[162:165], v[178:181], v[122:125]
	v_mfma_f32_16x16x32_bf16 v[118:121], v[170:173], v[178:181], v[118:121]
	v_mfma_f32_16x16x32_bf16 v[106:109], v[162:165], v[188:191], v[106:109]
	v_mfma_f32_16x16x32_bf16 v[102:105], v[170:173], v[188:191], v[102:105]
	v_mfma_f32_16x16x32_bf16 v[90:93], v[162:165], v[196:199], v[90:93]
	v_mfma_f32_16x16x32_bf16 v[86:89], v[170:173], v[196:199], v[86:89]
	v_mfma_f32_16x16x32_bf16 v[74:77], v[162:165], v[204:207], v[74:77]
	v_mfma_f32_16x16x32_bf16 v[70:73], v[170:173], v[204:207], v[70:73]
	s_setprio 0
	s_barrier
	s_add_i32 s24, s63, s1
	s_mov_b32 m0, s24
	s_nop 0
	global_load_lds_dwordx4 v0, s[38:39]
	s_add_i32 m0, s24, 0x2000
	s_add_u32 s24, s38, 0x40000
	s_addc_u32 s25, s39, 0
	s_add_i32 s3, s3, s1
	global_load_lds_dwordx4 v14, s[38:39]
	s_mov_b32 m0, s3
	s_nop 0
	global_load_lds_dwordx4 v0, s[24:25]
	s_add_i32 m0, s3, 0x2000
	s_nop 0
	global_load_lds_dwordx4 v14, s[24:25]
	s_mov_b32 m0, s28
	s_nop 0
	global_load_lds_dwordx4 v152, s[40:41]
	s_mov_b32 m0, s29
	s_nop 0
	global_load_lds_dwordx4 v150, s[40:41]
	ds_read_b128 v[174:177], v182 offset:16384
	ds_read_b128 v[178:181], v182 offset:17408
	ds_read_b128 v[184:187], v182 offset:18432
	ds_read_b128 v[188:191], v182 offset:19456
	ds_read_b128 v[192:195], v182 offset:20480
	ds_read_b128 v[196:199], v182 offset:21504
	ds_read_b128 v[200:203], v182 offset:22528
	ds_read_b128 v[204:207], v182 offset:23552
	s_waitcnt vmcnt(8)
	s_waitcnt lgkmcnt(0)
	s_barrier
	s_setprio 1
	s_waitcnt lgkmcnt(0)
	v_mfma_f32_16x16x32_bf16 v[66:69], v[134:137], v[174:177], v[66:69]
	v_mfma_f32_16x16x32_bf16 v[62:65], v[142:145], v[174:177], v[62:65]
	v_mfma_f32_16x16x32_bf16 v[50:53], v[134:137], v[184:187], v[50:53]
	v_mfma_f32_16x16x32_bf16 v[46:49], v[142:145], v[184:187], v[46:49]
	v_mfma_f32_16x16x32_bf16 v[34:37], v[134:137], v[192:195], v[34:37]
	v_mfma_f32_16x16x32_bf16 v[30:33], v[142:145], v[192:195], v[30:33]
	v_mfma_f32_16x16x32_bf16 v[18:21], v[134:137], v[200:203], v[18:21]
	v_mfma_f32_16x16x32_bf16 v[10:13], v[142:145], v[200:203], v[10:13]
	v_mfma_f32_16x16x32_bf16 v[66:69], v[138:141], v[178:181], v[66:69]
	v_mfma_f32_16x16x32_bf16 v[62:65], v[146:149], v[178:181], v[62:65]
	v_mfma_f32_16x16x32_bf16 v[50:53], v[138:141], v[188:191], v[50:53]
	v_mfma_f32_16x16x32_bf16 v[46:49], v[146:149], v[188:191], v[46:49]
	v_mfma_f32_16x16x32_bf16 v[34:37], v[138:141], v[196:199], v[34:37]
	v_mfma_f32_16x16x32_bf16 v[30:33], v[146:149], v[196:199], v[30:33]
	v_mfma_f32_16x16x32_bf16 v[18:21], v[138:141], v[204:207], v[18:21]
	v_mfma_f32_16x16x32_bf16 v[10:13], v[146:149], v[204:207], v[10:13]
	s_setprio 0
	s_setprio 1
	v_mfma_f32_16x16x32_bf16 v[58:61], v[158:161], v[174:177], v[58:61]
	v_mfma_f32_16x16x32_bf16 v[54:57], v[166:169], v[174:177], v[54:57]
	v_mfma_f32_16x16x32_bf16 v[42:45], v[158:161], v[184:187], v[42:45]
	v_mfma_f32_16x16x32_bf16 v[38:41], v[166:169], v[184:187], v[38:41]
	v_mfma_f32_16x16x32_bf16 v[26:29], v[158:161], v[192:195], v[26:29]
	v_mfma_f32_16x16x32_bf16 v[22:25], v[166:169], v[192:195], v[22:25]
	v_mfma_f32_16x16x32_bf16 v[6:9], v[158:161], v[200:203], v[6:9]
	v_mfma_f32_16x16x32_bf16 v[2:5], v[166:169], v[200:203], v[2:5]
	v_mfma_f32_16x16x32_bf16 v[58:61], v[162:165], v[178:181], v[58:61]
	v_mfma_f32_16x16x32_bf16 v[54:57], v[170:173], v[178:181], v[54:57]
	v_mfma_f32_16x16x32_bf16 v[42:45], v[162:165], v[188:191], v[42:45]
	v_mfma_f32_16x16x32_bf16 v[38:41], v[170:173], v[188:191], v[38:41]
	v_mfma_f32_16x16x32_bf16 v[26:29], v[162:165], v[196:199], v[26:29]
	v_mfma_f32_16x16x32_bf16 v[22:25], v[170:173], v[196:199], v[22:25]
	v_mfma_f32_16x16x32_bf16 v[6:9], v[162:165], v[204:207], v[6:9]
	v_mfma_f32_16x16x32_bf16 v[2:5], v[170:173], v[204:207], v[2:5]
	s_setprio 0
	s_barrier
	s_add_i32 s3, 0, 0x18000
	s_add_i32 s26, 0, 0x1c000
	s_add_u32 s24, s40, 0x40000
	s_addc_u32 s25, s41, 0
	s_mov_b32 m0, s42
	s_nop 0
	global_load_lds_dwordx4 v152, s[24:25]
	s_mov_b32 m0, s43
	s_nop 0
	global_load_lds_dwordx4 v150, s[24:25]
	v_add_u32_e32 v146, s3, v17
	v_add_u32_e32 v170, s26, v17
	ds_read_b128 v[134:137], v146
	ds_read_b128 v[138:141], v146 offset:1024
	ds_read_b128 v[142:145], v146 offset:2048
	ds_read_b128 v[146:149], v146 offset:3072
	ds_read_b128 v[158:161], v170
	ds_read_b128 v[162:165], v170 offset:1024
	ds_read_b128 v[166:169], v170 offset:2048
	ds_read_b128 v[170:173], v170 offset:3072
	ds_read_b128 v[174:177], v182 offset:32768
	ds_read_b128 v[178:181], v182 offset:33792
	ds_read_b128 v[184:187], v182 offset:34816
	ds_read_b128 v[188:191], v182 offset:35840
	ds_read_b128 v[192:195], v182 offset:36864
	ds_read_b128 v[196:199], v182 offset:37888
	ds_read_b128 v[200:203], v182 offset:38912
	ds_read_b128 v[204:207], v182 offset:39936
	s_waitcnt vmcnt(8)
	s_waitcnt lgkmcnt(0)
	s_barrier
	s_setprio 1
	s_waitcnt lgkmcnt(0)
	v_mfma_f32_16x16x32_bf16 v[130:133], v[134:137], v[174:177], v[130:133]
	v_mfma_f32_16x16x32_bf16 v[126:129], v[142:145], v[174:177], v[126:129]
	v_mfma_f32_16x16x32_bf16 v[114:117], v[134:137], v[184:187], v[114:117]
	v_mfma_f32_16x16x32_bf16 v[110:113], v[142:145], v[184:187], v[110:113]
	v_mfma_f32_16x16x32_bf16 v[98:101], v[134:137], v[192:195], v[98:101]
	v_mfma_f32_16x16x32_bf16 v[94:97], v[142:145], v[192:195], v[94:97]
	v_mfma_f32_16x16x32_bf16 v[82:85], v[134:137], v[200:203], v[82:85]
	v_mfma_f32_16x16x32_bf16 v[78:81], v[142:145], v[200:203], v[78:81]
	v_mfma_f32_16x16x32_bf16 v[130:133], v[138:141], v[178:181], v[130:133]
	v_mfma_f32_16x16x32_bf16 v[126:129], v[146:149], v[178:181], v[126:129]
	v_mfma_f32_16x16x32_bf16 v[114:117], v[138:141], v[188:191], v[114:117]
	v_mfma_f32_16x16x32_bf16 v[110:113], v[146:149], v[188:191], v[110:113]
	v_mfma_f32_16x16x32_bf16 v[98:101], v[138:141], v[196:199], v[98:101]
	v_mfma_f32_16x16x32_bf16 v[94:97], v[146:149], v[196:199], v[94:97]
	v_mfma_f32_16x16x32_bf16 v[82:85], v[138:141], v[204:207], v[82:85]
	v_mfma_f32_16x16x32_bf16 v[78:81], v[146:149], v[204:207], v[78:81]
	s_setprio 0
	s_setprio 1
	v_mfma_f32_16x16x32_bf16 v[122:125], v[158:161], v[174:177], v[122:125]
	v_mfma_f32_16x16x32_bf16 v[118:121], v[166:169], v[174:177], v[118:121]
	v_mfma_f32_16x16x32_bf16 v[106:109], v[158:161], v[184:187], v[106:109]
	v_mfma_f32_16x16x32_bf16 v[102:105], v[166:169], v[184:187], v[102:105]
	v_mfma_f32_16x16x32_bf16 v[90:93], v[158:161], v[192:195], v[90:93]
	v_mfma_f32_16x16x32_bf16 v[86:89], v[166:169], v[192:195], v[86:89]
	v_mfma_f32_16x16x32_bf16 v[74:77], v[158:161], v[200:203], v[74:77]
	v_mfma_f32_16x16x32_bf16 v[70:73], v[166:169], v[200:203], v[70:73]
	v_mfma_f32_16x16x32_bf16 v[122:125], v[162:165], v[178:181], v[122:125]
	v_mfma_f32_16x16x32_bf16 v[118:121], v[170:173], v[178:181], v[118:121]
	v_mfma_f32_16x16x32_bf16 v[106:109], v[162:165], v[188:191], v[106:109]
	v_mfma_f32_16x16x32_bf16 v[102:105], v[170:173], v[188:191], v[102:105]
	v_mfma_f32_16x16x32_bf16 v[90:93], v[162:165], v[196:199], v[90:93]
	v_mfma_f32_16x16x32_bf16 v[86:89], v[170:173], v[196:199], v[86:89]
	v_mfma_f32_16x16x32_bf16 v[74:77], v[162:165], v[204:207], v[74:77]
	v_mfma_f32_16x16x32_bf16 v[70:73], v[170:173], v[204:207], v[70:73]
	s_setprio 0
	s_barrier
	s_add_i32 s3, s3, s1
	s_mov_b32 m0, s3
	s_nop 0
	s_add_u32 s98, s38, s92
	s_addc_u32 s99, s39, s93
	global_load_lds_dwordx4 v0, s[98:99]
	s_add_i32 m0, s3, 0x2000
	s_add_u32 s24, s38, 0x40080
	s_addc_u32 s25, s39, 0
	s_add_i32 s3, s26, s1
	global_load_lds_dwordx4 v14, s[98:99]
	s_mov_b32 m0, s3
	s_nop 0
	global_load_lds_dwordx4 v0, s[24:25]
	s_add_i32 m0, s3, 0x2000
	s_nop 0
	global_load_lds_dwordx4 v14, s[24:25]
	s_mov_b32 m0, s44
	s_nop 0
	s_add_u32 s98, s40, s92
	s_addc_u32 s99, s41, s93
	global_load_lds_dwordx4 v152, s[98:99]
	s_mov_b32 m0, s45
	s_nop 0
	global_load_lds_dwordx4 v150, s[98:99]
	ds_read_b128 v[174:177], v182 offset:49152
	ds_read_b128 v[178:181], v182 offset:50176
	ds_read_b128 v[184:187], v182 offset:51200
	ds_read_b128 v[188:191], v182 offset:52224
	ds_read_b128 v[192:195], v182 offset:53248
	ds_read_b128 v[196:199], v182 offset:54272
	ds_read_b128 v[200:203], v182 offset:55296
	ds_read_b128 v[204:207], v182 offset:56320
	s_waitcnt vmcnt(8)
	s_waitcnt lgkmcnt(0)
	s_barrier
	s_setprio 1
	s_waitcnt lgkmcnt(0)
	v_mfma_f32_16x16x32_bf16 v[66:69], v[134:137], v[174:177], v[66:69]
	v_mfma_f32_16x16x32_bf16 v[62:65], v[142:145], v[174:177], v[62:65]
	v_mfma_f32_16x16x32_bf16 v[50:53], v[134:137], v[184:187], v[50:53]
	v_mfma_f32_16x16x32_bf16 v[46:49], v[142:145], v[184:187], v[46:49]
	v_mfma_f32_16x16x32_bf16 v[34:37], v[134:137], v[192:195], v[34:37]
	v_mfma_f32_16x16x32_bf16 v[30:33], v[142:145], v[192:195], v[30:33]
	v_mfma_f32_16x16x32_bf16 v[18:21], v[134:137], v[200:203], v[18:21]
	v_mfma_f32_16x16x32_bf16 v[10:13], v[142:145], v[200:203], v[10:13]
	v_mfma_f32_16x16x32_bf16 v[66:69], v[138:141], v[178:181], v[66:69]
	v_mfma_f32_16x16x32_bf16 v[62:65], v[146:149], v[178:181], v[62:65]
	v_mfma_f32_16x16x32_bf16 v[50:53], v[138:141], v[188:191], v[50:53]
	v_mfma_f32_16x16x32_bf16 v[46:49], v[146:149], v[188:191], v[46:49]
	v_mfma_f32_16x16x32_bf16 v[34:37], v[138:141], v[196:199], v[34:37]
	v_mfma_f32_16x16x32_bf16 v[30:33], v[146:149], v[196:199], v[30:33]
	v_mfma_f32_16x16x32_bf16 v[18:21], v[138:141], v[204:207], v[18:21]
	v_mfma_f32_16x16x32_bf16 v[10:13], v[146:149], v[204:207], v[10:13]
	s_setprio 0
	s_setprio 1
	v_mfma_f32_16x16x32_bf16 v[58:61], v[158:161], v[174:177], v[58:61]
	v_mfma_f32_16x16x32_bf16 v[54:57], v[166:169], v[174:177], v[54:57]
	v_mfma_f32_16x16x32_bf16 v[42:45], v[158:161], v[184:187], v[42:45]
	v_mfma_f32_16x16x32_bf16 v[38:41], v[166:169], v[184:187], v[38:41]
	v_mfma_f32_16x16x32_bf16 v[26:29], v[158:161], v[192:195], v[26:29]
	v_mfma_f32_16x16x32_bf16 v[22:25], v[166:169], v[192:195], v[22:25]
	v_mfma_f32_16x16x32_bf16 v[6:9], v[158:161], v[200:203], v[6:9]
	v_mfma_f32_16x16x32_bf16 v[2:5], v[166:169], v[200:203], v[2:5]
	v_mfma_f32_16x16x32_bf16 v[58:61], v[162:165], v[178:181], v[58:61]
	v_mfma_f32_16x16x32_bf16 v[54:57], v[170:173], v[178:181], v[54:57]
	v_mfma_f32_16x16x32_bf16 v[42:45], v[162:165], v[188:191], v[42:45]
	v_mfma_f32_16x16x32_bf16 v[38:41], v[170:173], v[188:191], v[38:41]
	v_mfma_f32_16x16x32_bf16 v[26:29], v[162:165], v[196:199], v[26:29]
	v_mfma_f32_16x16x32_bf16 v[22:25], v[170:173], v[196:199], v[22:25]
	v_mfma_f32_16x16x32_bf16 v[6:9], v[162:165], v[204:207], v[6:9]
	v_mfma_f32_16x16x32_bf16 v[2:5], v[170:173], v[204:207], v[2:5]
	s_setprio 0
	s_barrier
	s_add_i32 s50, s50, 2
	s_add_u32 s36, s36, 0x100
	s_addc_u32 s37, s37, 0
	s_add_u32 s48, s48, 0x100
	s_addc_u32 s49, s49, 0
	s_cmp_gt_u32 s50, 13
	s_cbranch_scc0 .LBB0_817
	s_and_b64 vcc, exec, s[12:13]
	s_cbranch_vccz .LBB0_820
	s_barrier
